# DeltaNet chunk scan: next-chunk prefetch loads no longer issued as one 12-instruction burst before the barrier - 8 of them moved behind the barrier so the address pipeline drains them while the MFMA s
# speedup vs baseline: 1.0237x; 1.0237x over previous
.LBB0_286:
	v_add_u32_e32 v101, v43, v107
	s_add_u32 s18, s94, s10
	s_waitcnt lgkmcnt(0)
	s_barrier
	s_waitcnt vmcnt(4)
	v_perm_b32 v99, v147, v103, s78
	v_perm_b32 v97, v146, v105, s78
	ds_write_b128 v76, v[2:5]
	ds_write_b128 v101, v[6:9] offset:34816
	ds_write_b128 v76, v[10:13] offset:53248
	ds_write_b128 v78, v[14:17]
	ds_write_b128 v145, v[18:21] offset:34816
	ds_write_b128 v78, v[22:25] offset:53248
	ds_write_b128 v129, v[26:29]
	v_lshl_add_u64 v[2:3], s[94:95], 0, v[108:109]
	v_lshl_add_u64 v[6:7], s[94:95], 0, v[110:111]
	v_lshl_add_u64 v[10:11], s[94:95], 0, v[126:127]
	v_lshl_add_u64 v[14:15], s[94:95], 0, v[114:115]
	v_lshl_add_u64 v[18:19], s[94:95], 0, v[116:117]
	v_lshl_add_u64 v[22:23], s[94:95], 0, v[124:125]
	v_lshl_add_u64 v[26:27], s[94:95], 0, v[120:121]
	v_lshl_add_u64 v[146:147], s[94:95], 0, v[122:123]
	v_lshl_add_u64 v[148:149], s[94:95], 0, v[118:119]
	s_addc_u32 s19, s95, s12
	v_mov_b32_e32 v128, v106
	global_load_dwordx4 v[2:5], v[2:3], off
	v_pk_mul_f32 v[32:33], v[32:33], v[128:129] op_sel_hi:[1,0]
	global_load_dwordx4 v[6:9], v[6:7], off
	v_pk_mul_f32 v[30:31], v[30:31], v[128:129] op_sel_hi:[1,0]
	global_load_dwordx4 v[10:13], v[10:11], off
	v_pk_mul_f32 v[36:37], v[36:37], v[128:129] op_sel_hi:[1,0]
	global_load_dwordx4 v[14:17], v[14:15], off
	v_pk_mul_f32 v[34:35], v[34:35], v[128:129] op_sel_hi:[1,0]
	s_add_u32 s10, s10, 4
	s_addc_u32 s12, s12, 0
	s_add_i32 s8, s8, -1
	s_nop 0
	s_waitcnt lgkmcnt(0)
	s_barrier
	global_load_dwordx4 v[18:21], v[18:19], off
	global_load_dwordx4 v[22:25], v[22:23], off
	global_load_dwordx4 v[26:29], v[26:27], off
	global_load_ushort v103, v[146:147], off
	global_load_ushort v147, v[148:149], off offset:-256
	global_load_ushort v105, v[148:149], off
	global_load_ushort v146, v[148:149], off offset:256
	global_load_dword v106, v1, s[18:19]
	ds_read_b128 v[180:183], v130
	ds_read_b128 v[196:199], v131 offset:53248
	ds_read_b128 v[184:187], v130 offset:64
	ds_read_b128 v[200:203], v131 offset:53312
	ds_read_b128 v[188:191], v130 offset:128
	ds_read_b128 v[208:211], v131 offset:53376
	ds_read_b128 v[192:195], v130 offset:192
	ds_read_b128 v[212:215], v131 offset:53440
	ds_read_b128 v[216:219], v131
	ds_read_b128 v[220:223], v131 offset:64
	ds_read_b128 v[224:227], v131 offset:128
	ds_read_b128 v[228:231], v131 offset:192
	v_lshl_add_u64 v[108:109], v[108:109], 0, s[56:57]
	v_lshl_add_u64 v[110:111], v[110:111], 0, s[56:57]
	v_lshl_add_u64 v[114:115], v[114:115], 0, s[56:57]
	s_waitcnt lgkmcnt(10)
	v_mfma_f32_16x16x32_bf16 v[152:155], v[196:199], v[180:183], 0
	ds_read_b128 v[232:235], v133
	v_lshl_add_u64 v[116:117], v[116:117], 0, s[56:57]
	s_waitcnt lgkmcnt(9)
	v_mfma_f32_16x16x32_bf16 v[152:155], v[200:203], v[184:187], v[152:155]
	ds_read_b128 v[236:239], v133 offset:64
	v_lshl_add_u64 v[118:119], v[118:119], 0, s[4:5]
	s_waitcnt lgkmcnt(8)
	v_mfma_f32_16x16x32_bf16 v[152:155], v[208:211], v[188:191], v[152:155]
	ds_read_b128 v[240:243], v135 offset:34816
	v_lshl_add_u64 v[120:121], v[120:121], 0, s[56:57]
	s_waitcnt lgkmcnt(7)
	v_mfma_f32_16x16x32_bf16 v[152:155], v[212:215], v[192:195], v[152:155]
	ds_read_b128 v[176:179], v135 offset:34880
	v_lshl_add_u64 v[122:123], v[122:123], 0, s[4:5]
	s_waitcnt lgkmcnt(7)
	v_mfma_f32_16x16x32_bf16 v[148:151], v[216:219], v[180:183], 0
	v_lshl_add_u64 v[124:125], v[124:125], 0, s[4:5]
	s_waitcnt lgkmcnt(6)
	v_mfma_f32_16x16x32_bf16 v[148:151], v[220:223], v[184:187], v[148:151]
	v_lshl_add_u64 v[126:127], v[126:127], 0, s[4:5]
	s_waitcnt lgkmcnt(5)
	v_mfma_f32_16x16x32_bf16 v[148:151], v[224:227], v[188:191], v[148:151]
	v_and_b32_e32 v157, 0xffff0000, v99
	s_waitcnt lgkmcnt(4)
	v_mfma_f32_16x16x32_bf16 v[148:151], v[228:231], v[192:195], v[148:151]
	v_lshlrev_b32_e32 v156, 16, v99
	v_and_b32_e32 v159, 0xffff0000, v97
	v_lshlrev_b32_e32 v158, 16, v97
	v_pk_add_f32 v[152:153], v[156:157], v[152:153] neg_lo:[0,1] neg_hi:[0,1]
	v_pk_add_f32 v[154:155], v[158:159], v[154:155] neg_lo:[0,1] neg_hi:[0,1]
	v_cvt_pk_bf16_f32 v152, v152, v153
	v_cvt_pk_bf16_f32 v153, v154, v155
	ds_write_b64 v132, v[152:153]
	s_waitcnt lgkmcnt(0)
	s_barrier
	ds_read_b128 v[180:183], v134
	ds_read_b128 v[184:187], v134 offset:64
	ds_read_b128 v[188:191], v136
	ds_read_b128 v[192:195], v136 offset:64
	ds_read_b128 v[196:199], v136 offset:2304
	ds_read_b128 v[200:203], v136 offset:2368
	s_waitcnt lgkmcnt(5)
	v_mfma_f32_16x16x32_bf16 v[148:151], v[232:235], v[180:183], v[148:151]
	v_lshl_add_u64 v[152:153], s[94:95], 0, v[112:113]
	s_waitcnt lgkmcnt(4)
	v_mfma_f32_16x16x32_bf16 v[148:151], v[236:239], v[184:187], v[148:151]
	v_lshl_add_u64 v[112:113], v[112:113], 0, s[4:5]
	s_waitcnt lgkmcnt(3)
	v_mfma_f32_16x16x32_bf16 v[30:33], v[240:243], v[188:191], v[30:33]
	s_waitcnt lgkmcnt(2)
	v_mfma_f32_16x16x32_bf16 v[30:33], v[176:179], v[192:195], v[30:33]
	s_waitcnt lgkmcnt(1)
	v_mfma_f32_16x16x32_bf16 v[34:37], v[240:243], v[196:199], v[34:37]
	s_waitcnt lgkmcnt(0)
	v_mfma_f32_16x16x32_bf16 v[34:37], v[176:179], v[200:203], v[34:37]
	s_nop 0
	v_cvt_pk_bf16_f32 v97, v148, s0
	global_store_short v[152:153], v97, off offset:-512
	v_cvt_pk_bf16_f32 v97, v149, s0
	global_store_short v[152:153], v97, off offset:-256
	v_cvt_pk_bf16_f32 v97, v150, s0
	global_store_short v[152:153], v97, off
	v_cvt_pk_bf16_f32 v97, v151, s0
	global_store_short v[152:153], v97, off offset:256
	v_cvt_pk_bf16_f32 v156, v30, v31
	v_cvt_pk_bf16_f32 v157, v32, v33
	ds_write_b64 v137, v[156:157]
	v_cvt_pk_bf16_f32 v158, v34, v35
	v_cvt_pk_bf16_f32 v159, v36, v37
	ds_write_b64 v137, v[158:159] offset:4352
	s_cmp_eq_u32 s8, 0
	s_cbranch_scc0 .LBB0_286
	s_waitcnt lgkmcnt(0)
	s_barrier
	s_waitcnt vmcnt(4)
	ds_write_b128 v76, v[2:5]
	ds_write_b128 v101, v[6:9] offset:34816
	ds_write_b128 v76, v[10:13] offset:53248
	ds_write_b128 v78, v[14:17]
	ds_write_b128 v145, v[18:21] offset:34816
	ds_write_b128 v78, v[22:25] offset:53248
	ds_write_b128 v129, v[26:29]
	s_waitcnt lgkmcnt(0)
	s_barrier
	ds_read_b128 v[2:5], v131 offset:53248
	ds_read_b128 v[6:9], v130
	ds_read_b128 v[10:13], v130 offset:64
	ds_read_b128 v[14:17], v131 offset:53312
	s_waitcnt lgkmcnt(2)
	v_mfma_f32_16x16x32_bf16 v[2:5], v[2:5], v[6:9], 0
	ds_read_b128 v[18:21], v131
	ds_read_b128 v[22:25], v131 offset:64
	v_lshlrev_b32_e32 v27, 16, v147
	v_lshlrev_b32_e32 v26, 16, v103
	s_waitcnt lgkmcnt(2)
	v_mfma_f32_16x16x32_bf16 v[2:5], v[14:17], v[10:13], v[2:5]
	ds_read_b128 v[14:17], v131 offset:53376
	s_lshl_b32 s8, s11, 1
	s_add_u32 s6, s6, s8
	s_waitcnt lgkmcnt(2)
	v_mfma_f32_16x16x32_bf16 v[6:9], v[18:21], v[6:9], 0
	s_addc_u32 s7, s7, 0
	s_add_i32 s2, s2, s50
	s_cmpk_gt_i32 s2, 0xff
	s_waitcnt lgkmcnt(1)
	v_mfma_f32_16x16x32_bf16 v[6:9], v[22:25], v[10:13], v[6:9]
	ds_read_b128 v[10:13], v131 offset:53440
	ds_read_b128 v[18:21], v130 offset:128
	ds_read_b128 v[22:25], v130 offset:192
	s_waitcnt lgkmcnt(1)
	v_mfma_f32_16x16x32_bf16 v[2:5], v[14:17], v[18:21], v[2:5]
	s_waitcnt lgkmcnt(0)
	v_mfma_f32_16x16x32_bf16 v[2:5], v[10:13], v[22:25], v[2:5]
	ds_read_b128 v[10:13], v131 offset:128
	ds_read_b128 v[14:17], v131 offset:192
	s_waitcnt lgkmcnt(1)
	v_mfma_f32_16x16x32_bf16 v[6:9], v[10:13], v[18:21], v[6:9]
	s_nop 3
	v_add_f32_e64 v2, v26, -v2
	v_add_f32_e64 v3, v27, -v3
	v_lshlrev_b32_e32 v27, 16, v146
	v_lshlrev_b32_e32 v26, 16, v105
	v_pk_add_f32 v[4:5], v[26:27], v[4:5] neg_lo:[0,1] neg_hi:[0,1]
	v_cvt_pk_bf16_f32 v2, v2, v3
	v_cvt_pk_bf16_f32 v3, v4, v5
	ds_write_b64 v132, v[2:3]
	s_waitcnt lgkmcnt(0)
	s_barrier
	ds_read_b128 v[2:5], v133
	ds_read_b128 v[10:13], v134
	ds_read_b128 v[18:21], v133 offset:64
	v_mfma_f32_16x16x32_bf16 v[6:9], v[14:17], v[22:25], v[6:9]
	ds_read_b128 v[14:17], v134 offset:64
	v_mov_b32_e32 v105, v1
	s_waitcnt lgkmcnt(2)
	v_mfma_f32_16x16x32_bf16 v[2:5], v[2:5], v[10:13], v[6:9]
	s_nop 3
	v_lshl_add_u64 v[6:7], s[6:7], 0, v[0:1]
	v_lshl_add_u64 v[6:7], v[6:7], 0, v[104:105]
	s_waitcnt lgkmcnt(0)
	v_mfma_f32_16x16x32_bf16 v[2:5], v[18:21], v[14:17], v[2:5]
	s_mov_b64 s[6:7], 0xfc000
	v_lshl_add_u64 v[108:109], v[6:7], 0, s[6:7]
	v_lshl_add_u64 v[6:7], v[66:67], 1, v[108:109]
	s_waitcnt vmcnt(4)
	v_pk_mul_f32 v[20:21], v[106:107], v[32:33] op_sel_hi:[0,1]
	v_pk_mul_f32 v[18:19], v[106:107], v[30:31] op_sel_hi:[0,1]
	s_nop 1
	v_cvt_pk_bf16_f32 v2, v2, s0
	global_store_short v[6:7], v2, off
	ds_read_b128 v[6:9], v135 offset:34816
	v_cvt_pk_bf16_f32 v10, v3, s0
	v_lshl_add_u64 v[2:3], v[70:71], 1, v[108:109]
	global_store_short v[2:3], v10, off
	ds_read_b128 v[10:13], v135 offset:34880
	ds_read_b128 v[14:17], v136
	ds_read_b128 v[22:25], v136 offset:64
	s_waitcnt lgkmcnt(1)
	v_mfma_f32_16x16x32_bf16 v[14:17], v[6:9], v[14:17], v[18:21]
	s_nop 2
	ds_read_b128 v[18:21], v136 offset:2304
	ds_read_b128 v[26:29], v136 offset:2368
	v_cvt_pk_bf16_f32 v4, v4, s0
	s_waitcnt lgkmcnt(2)
	v_mfma_f32_16x16x32_bf16 v[14:17], v[10:13], v[22:25], v[14:17]
	v_mul_f32_e64 v24, v106, v36
	v_mul_f32_e64 v25, v106, v37
	v_pk_mul_f32 v[22:23], v[106:107], v[34:35] op_sel_hi:[0,1]
	v_lshl_add_u64 v[2:3], v[72:73], 1, v[108:109]
	global_store_short v[2:3], v4, off
	s_waitcnt lgkmcnt(1)
	v_mfma_f32_16x16x32_bf16 v[6:9], v[6:9], v[18:21], v[22:25]
	v_cvt_pk_bf16_f32 v4, v5, s0
	v_lshl_add_u64 v[2:3], v[74:75], 1, v[108:109]
	global_store_short v[2:3], v4, off
	s_waitcnt lgkmcnt(0)
	v_mfma_f32_16x16x32_bf16 v[2:5], v[10:13], v[26:29], v[6:9]
	s_nop 2
	v_cvt_pk_bf16_f32 v6, v14, v15
	v_cvt_pk_bf16_f32 v7, v16, v17
	s_nop 2
	v_cvt_pk_bf16_f32 v2, v2, v3
	v_cvt_pk_bf16_f32 v3, v4, v5
	ds_write_b64 v137, v[6:7]
	ds_write_b64 v137, v[2:3] offset:4352
	s_cbranch_scc0 .LBB0_282
